# attention (prompt): own staging path - next tile's V loads issued before the first barrier and K loads right after K staging (nearly a full tile of prefetch lead), 2 barriers per tile
# baseline (speedup 1.0000x reference)
; #define LAS __attribute__((address_space(3)))
; __device__ __forceinline__ void attn_item(const Params& P, int l, LAS unsigned char* lds, int item, const int wv) {
;     ...
;     for (int jt = 0; jt < nkt; ++jt) {
;         __syncthreads();
; #pragma unroll
;         for (int i = 0; i < 4; ++i) {
;             { const int idx = tid + 512 * i, key = idx >> 5, hc = idx & 31, hh = hc >> 4, ch = hc & 15;
;               *(LAS u32x4*)(Kl + (hh * 64 + key) * 136 + 8 * ch) = kreg[i]; }
;             { const int idx = tid + 512 * i, key = idx & 63, hc = idx >> 6, hh = hc >> 4, ch = hc & 15; const u32x4 vv = vreg[i];
;               LAS bf16_t* d = Vt + (hh * 128 + 8 * ch) * 72 + key;
;               d[0 * 72] = (bf16_t)(vv.x & 0xffffu); d[1 * 72] = (bf16_t)(vv.x >> 16); d[2 * 72] = (bf16_t)(vv.y & 0xffffu); d[3 * 72] = (bf16_t)(vv.y >> 16);
;               d[4 * 72] = (bf16_t)(vv.z & 0xffffu); d[5 * 72] = (bf16_t)(vv.z >> 16); d[6 * 72] = (bf16_t)(vv.w & 0xffffu); d[7 * 72] = (bf16_t)(vv.w >> 16); }
;         }
;         if (jt + 1 < nkt) ATT_LOAD(jt + 1);
.LBB0_352:
	s_and_b64 vcc, exec, s[38:39]
	s_cbranch_vccnz .Lattn_nobounce
	v_and_b32_e32 v82, 31, v114
	v_mul_u32_u24_e32 v83, 0x210, v102
	v_lshl_add_u32 v82, v82, 4, v83
	v_add_u32_e32 v82, 0x12800, v82
	v_mul_u32_u24_e32 v84, 0x210, v114
	v_lshrrev_b32_e32 v85, 1, v102
	v_lshl_add_u32 v84, v85, 4, v84
	v_add_u32_e32 v84, 0x12800, v84
	s_add_i32 s20, s21, 1
	s_waitcnt vmcnt(0)
	ds_write_b128 v82, v[220:223]
	ds_write_b128 v82, v[224:227] offset:8448
	ds_write_b128 v82, v[228:231] offset:16896
	ds_write_b128 v82, v[232:235] offset:25344
	s_cmp_ge_i32 s20, s25
	s_cbranch_scc1 .Lattn_p_nopf1
	s_mov_b64 s[14:15], 0x1000
	v_add_u32_e32 v86, s19, v163
	v_add_u32_e32 v88, s19, v162
	v_add_u32_e32 v90, s19, v161
	v_add_u32_e32 v92, s19, v160
	v_mad_i64_i32 v[86:87], vcc, v86, s13, v[140:141]
	v_mad_i64_i32 v[88:89], vcc, v88, s13, v[140:141]
	v_mad_i64_i32 v[90:91], vcc, v90, s13, v[140:141]
	v_mad_i64_i32 v[92:93], vcc, v92, s13, v[140:141]
	v_lshl_add_u64 v[86:87], v[86:87], 0, s[14:15]
	v_lshl_add_u64 v[88:89], v[88:89], 0, s[14:15]
	v_lshl_add_u64 v[90:91], v[90:91], 0, s[14:15]
	v_lshl_add_u64 v[92:93], v[92:93], 0, s[14:15]
	global_load_dwordx4 v[220:223], v[86:87], off
	global_load_dwordx4 v[224:227], v[88:89], off
	global_load_dwordx4 v[228:231], v[90:91], off
	global_load_dwordx4 v[232:235], v[92:93], off
.Lattn_p_nopf1:
	s_waitcnt lgkmcnt(0)
	s_barrier
	ds_read_b128 v[22:25], v84
	ds_read_b128 v[30:33], v84 offset:128
	ds_read_b128 v[38:41], v84 offset:256
	ds_read_b128 v[46:49], v84 offset:384
	ds_write_b128 v165, v[18:21]
	ds_write_b128 v167, v[26:29]
	ds_write_b128 v169, v[34:37]
	ds_write_b128 v171, v[42:45]
	s_cmp_ge_i32 s20, s25
	s_cbranch_scc1 .Lattn_p_nopf2
	v_add_u32_e32 v18, s19, v163
	v_add_u32_e32 v26, s19, v162
	v_add_u32_e32 v34, s19, v161
	v_add_u32_e32 v44, s19, v160
	v_mad_i64_i32 v[18:19], vcc, v18, s13, v[140:141]
	v_mad_i64_i32 v[26:27], vcc, v26, s13, v[140:141]
	v_mad_i64_i32 v[34:35], vcc, v34, s13, v[140:141]
	v_mad_i64_i32 v[44:45], vcc, v44, s13, v[140:141]
	global_load_dwordx4 v[18:21], v[18:19], off offset:2048
	global_load_dwordx4 v[26:29], v[26:27], off offset:2048
	global_load_dwordx4 v[34:37], v[34:35], off offset:2048
	global_load_dwordx4 v[42:45], v[44:45], off offset:2048
.Lattn_p_nopf2:
	s_waitcnt lgkmcnt(4)
	ds_write_b16 v166, v22 offset:34816
	ds_write_b16_d16_hi v166, v22 offset:34960
	ds_write_b16 v166, v23 offset:35104
	ds_write_b16_d16_hi v166, v23 offset:35248
	ds_write_b16 v166, v24 offset:35392
	ds_write_b16_d16_hi v166, v24 offset:35536
	ds_write_b16 v166, v25 offset:35680
	ds_write_b16_d16_hi v166, v25 offset:35824
	ds_write_b16 v168, v30 offset:34816
	ds_write_b16_d16_hi v168, v30 offset:34960
	ds_write_b16 v168, v31 offset:35104
	ds_write_b16_d16_hi v168, v31 offset:35248
	ds_write_b16 v168, v32 offset:35392
	ds_write_b16_d16_hi v168, v32 offset:35536
	ds_write_b16 v168, v33 offset:35680
	ds_write_b16_d16_hi v168, v33 offset:35824
	ds_write_b16 v170, v38 offset:34816
	ds_write_b16_d16_hi v170, v38 offset:34960
	ds_write_b16 v170, v39 offset:35104
	ds_write_b16_d16_hi v170, v39 offset:35248
	ds_write_b16 v170, v40 offset:35392
	ds_write_b16_d16_hi v170, v40 offset:35536
	ds_write_b16 v170, v41 offset:35680
	ds_write_b16_d16_hi v170, v41 offset:35824
	ds_write_b16 v172, v46 offset:34816
	ds_write_b16_d16_hi v172, v46 offset:34960
	ds_write_b16 v172, v47 offset:35104
	ds_write_b16_d16_hi v172, v47 offset:35248
	ds_write_b16 v172, v48 offset:35392
	ds_write_b16_d16_hi v172, v48 offset:35536
	ds_write_b16 v172, v49 offset:35680
	ds_write_b16_d16_hi v172, v49 offset:35824
	s_branch .LBB0_376

; __device__ __forceinline__ void attn_item(const Params& P, int l, LAS unsigned char* lds, int item, const int wv) {
;     ...
;     ATT_LOAD(0);
.LBB0_390:
	v_and_or_b32 v8, v50, 63, s34
	v_mov_b64_e32 v[42:43], s[30:31]
	v_mad_u64_u32 v[18:19], s[8:9], v8, s13, v[42:43]
	s_lshl_b32 s82, s28, 8
	v_lshl_add_u64 v[18:19], v[18:19], 0, s[82:83]
	s_mov_b64 s[8:9], 0x1000
	v_add_u32_e32 v8, s34, v102
	v_add_u32_e32 v26, s34, v106
	v_add_u32_e32 v34, s34, v108
	v_add_u32_e32 v46, s34, v110
	v_lshl_add_u64 v[44:45], v[18:19], 0, s[8:9]
	v_mad_i64_i32 v[18:19], s[8:9], v8, s13, v[42:43]
	v_mad_i64_i32 v[26:27], s[8:9], v26, s13, v[42:43]
	v_and_b32_e32 v28, -8, v57
	v_mad_i64_i32 v[34:35], s[8:9], v34, s13, v[42:43]
	v_and_b32_e32 v36, -8, v56
	v_mad_i64_i32 v[42:43], s[8:9], v46, s13, v[42:43]
	v_and_b32_e32 v46, -8, v55
	v_lshl_add_u64 v[18:19], v[18:19], 0, s[82:83]
	v_and_b32_e32 v8, 0x1f0, v61
	v_ashrrev_i32_e32 v105, 31, v104
	v_lshl_add_u64 v[26:27], v[26:27], 0, s[82:83]
	v_ashrrev_i32_e32 v29, 31, v28
	v_lshl_add_u64 v[34:35], v[34:35], 0, s[82:83]
	v_ashrrev_i32_e32 v37, 31, v36
	v_lshl_add_u64 v[42:43], v[42:43], 0, s[82:83]
	v_ashrrev_i32_e32 v47, 31, v46
	v_lshl_add_u64 v[18:19], v[18:19], 0, v[8:9]
	v_lshl_add_u64 v[22:23], v[104:105], 1, v[44:45]
	v_lshl_add_u64 v[26:27], v[26:27], 0, v[8:9]
	v_lshl_add_u64 v[30:31], v[28:29], 1, v[44:45]
	v_lshl_add_u64 v[34:35], v[34:35], 0, v[8:9]
	v_lshl_add_u64 v[38:39], v[36:37], 1, v[44:45]
	v_lshl_add_u64 v[42:43], v[42:43], 0, v[8:9]
	v_lshl_add_u64 v[46:47], v[46:47], 1, v[44:45]
	s_mov_b64 s[8:9], 0x1000
	v_lshl_add_u64 v[22:23], v[18:19], 0, s[8:9]
	v_lshl_add_u64 v[30:31], v[26:27], 0, s[8:9]
	v_lshl_add_u64 v[38:39], v[34:35], 0, s[8:9]
	v_lshl_add_u64 v[46:47], v[42:43], 0, s[8:9]
	global_load_dwordx4 v[18:21], v[18:19], off offset:2048
	s_nop 0
	global_load_dwordx4 v[220:223], v[22:23], off
	s_nop 0
	global_load_dwordx4 v[26:29], v[26:27], off offset:2048
	s_nop 0
	global_load_dwordx4 v[224:227], v[30:31], off
	s_nop 0
	global_load_dwordx4 v[34:37], v[34:35], off offset:2048
	s_nop 0
	global_load_dwordx4 v[228:231], v[38:39], off
	s_nop 0
	global_load_dwordx4 v[42:45], v[42:43], off offset:2048
	s_nop 0
	global_load_dwordx4 v[232:235], v[46:47], off
	v_ashrrev_i32_e32 v103, 31, v102
	s_cbranch_execnz .LBB0_350
